# K-loops: per-segment setprio flips removed + one static s_setprio 1 for waves 4-7 before each K-loop (reset at loop exit)
# baseline (speedup 1.0000x reference)
.LBB0_164:
	s_ashr_i32 s61, s60, 31
	s_lshl_b64 s[12:13], s[60:61], 20
	s_add_u32 s64, s24, s12
	s_addc_u32 s65, s25, s13
	s_and_b64 s[12:13], s[6:7], exec
	s_cselect_b32 s9, s65, s21
	s_cselect_b32 s61, s64, s20
	s_ashr_i32 s63, s62, 31
	s_lshl_b64 s[12:13], s[62:63], 20
	s_add_u32 s66, s42, s12
	s_addc_u32 s67, s43, s13
	s_and_b64 s[12:13], s[6:7], exec
	s_cselect_b32 s63, s67, s1
	s_cselect_b32 s75, s66, s0
	s_add_u32 s70, s20, 0x80080
	s_addc_u32 s71, s21, 0
	s_add_u32 s20, s0, 0x100
	v_mov_b32_e32 v2, 0
	s_addc_u32 s21, s1, 0
	s_mov_b32 s76, -2
	v_mov_b32_e32 v3, v2
	v_mov_b32_e32 v4, v2
	v_mov_b32_e32 v5, v2
	v_mov_b32_e32 v6, v2
	v_mov_b32_e32 v7, v2
	v_mov_b32_e32 v8, v2
	v_mov_b32_e32 v9, v2
	v_mov_b32_e32 v18, v2
	v_mov_b32_e32 v19, v2
	v_mov_b32_e32 v20, v2
	v_mov_b32_e32 v21, v2
	v_mov_b32_e32 v22, v2
	v_mov_b32_e32 v23, v2
	v_mov_b32_e32 v24, v2
	v_mov_b32_e32 v25, v2
	v_mov_b32_e32 v34, v2
	v_mov_b32_e32 v35, v2
	v_mov_b32_e32 v36, v2
	v_mov_b32_e32 v37, v2
	v_mov_b32_e32 v38, v2
	v_mov_b32_e32 v39, v2
	v_mov_b32_e32 v40, v2
	v_mov_b32_e32 v41, v2
	v_mov_b32_e32 v50, v2
	v_mov_b32_e32 v51, v2
	v_mov_b32_e32 v52, v2
	v_mov_b32_e32 v53, v2
	v_mov_b32_e32 v54, v2
	v_mov_b32_e32 v55, v2
	v_mov_b32_e32 v56, v2
	v_mov_b32_e32 v57, v2
	v_mov_b32_e32 v10, v2
	v_mov_b32_e32 v11, v2
	v_mov_b32_e32 v12, v2
	v_mov_b32_e32 v13, v2
	v_mov_b32_e32 v14, v2
	v_mov_b32_e32 v15, v2
	v_mov_b32_e32 v16, v2
	v_mov_b32_e32 v17, v2
	v_mov_b32_e32 v26, v2
	v_mov_b32_e32 v27, v2
	v_mov_b32_e32 v28, v2
	v_mov_b32_e32 v29, v2
	v_mov_b32_e32 v30, v2
	v_mov_b32_e32 v31, v2
	v_mov_b32_e32 v32, v2
	v_mov_b32_e32 v33, v2
	v_mov_b32_e32 v42, v2
	v_mov_b32_e32 v43, v2
	v_mov_b32_e32 v44, v2
	v_mov_b32_e32 v45, v2
	v_mov_b32_e32 v46, v2
	v_mov_b32_e32 v47, v2
	v_mov_b32_e32 v48, v2
	v_mov_b32_e32 v49, v2
	v_mov_b32_e32 v58, v2
	v_mov_b32_e32 v59, v2
	v_mov_b32_e32 v60, v2
	v_mov_b32_e32 v61, v2
	v_mov_b32_e32 v62, v2
	v_mov_b32_e32 v63, v2
	v_mov_b32_e32 v64, v2
	v_mov_b32_e32 v65, v2
	v_mov_b32_e32 v66, v2
	v_mov_b32_e32 v67, v2
	v_mov_b32_e32 v68, v2
	v_mov_b32_e32 v69, v2
	v_mov_b32_e32 v70, v2
	v_mov_b32_e32 v71, v2
	v_mov_b32_e32 v72, v2
	v_mov_b32_e32 v73, v2
	v_mov_b32_e32 v82, v2
	v_mov_b32_e32 v83, v2
	v_mov_b32_e32 v84, v2
	v_mov_b32_e32 v85, v2
	v_mov_b32_e32 v86, v2
	v_mov_b32_e32 v87, v2
	v_mov_b32_e32 v88, v2
	v_mov_b32_e32 v89, v2
	v_mov_b32_e32 v98, v2
	v_mov_b32_e32 v99, v2
	v_mov_b32_e32 v100, v2
	v_mov_b32_e32 v101, v2
	v_mov_b32_e32 v102, v2
	v_mov_b32_e32 v103, v2
	v_mov_b32_e32 v104, v2
	v_mov_b32_e32 v105, v2
	v_mov_b32_e32 v130, v2
	v_mov_b32_e32 v131, v2
	v_mov_b32_e32 v132, v2
	v_mov_b32_e32 v133, v2
	v_mov_b32_e32 v134, v2
	v_mov_b32_e32 v135, v2
	v_mov_b32_e32 v136, v2
	v_mov_b32_e32 v137, v2
	v_mov_b32_e32 v74, v2
	v_mov_b32_e32 v75, v2
	v_mov_b32_e32 v76, v2
	v_mov_b32_e32 v77, v2
	v_mov_b32_e32 v78, v2
	v_mov_b32_e32 v79, v2
	v_mov_b32_e32 v80, v2
	v_mov_b32_e32 v81, v2
	v_mov_b32_e32 v90, v2
	v_mov_b32_e32 v91, v2
	v_mov_b32_e32 v92, v2
	v_mov_b32_e32 v93, v2
	v_mov_b32_e32 v94, v2
	v_mov_b32_e32 v95, v2
	v_mov_b32_e32 v96, v2
	v_mov_b32_e32 v97, v2
	v_mov_b32_e32 v106, v2
	v_mov_b32_e32 v107, v2
	v_mov_b32_e32 v108, v2
	v_mov_b32_e32 v109, v2
	v_mov_b32_e32 v110, v2
	v_mov_b32_e32 v111, v2
	v_mov_b32_e32 v112, v2
	v_mov_b32_e32 v113, v2
	v_mov_b32_e32 v138, v2
	v_mov_b32_e32 v139, v2
	v_mov_b32_e32 v140, v2
	v_mov_b32_e32 v141, v2
	v_mov_b32_e32 v142, v2
	v_mov_b32_e32 v143, v2
	v_mov_b32_e32 v144, v2
	v_mov_b32_e32 v145, v2
	s_cmp_eq_u64 s[56:57], 0
	s_cbranch_scc0 .Lprio_p1
	s_setprio 1
.Lprio_p1:
.LBB0_165:
	ds_read_b128 v[114:117], v177
	ds_read_b128 v[118:121], v177 offset:1024
	ds_read_b128 v[122:125], v177 offset:2048
	ds_read_b128 v[126:129], v177 offset:3072
	ds_read_b128 v[182:185], v178
	ds_read_b128 v[186:189], v178 offset:1024
	ds_read_b128 v[190:193], v178 offset:2048
	ds_read_b128 v[194:197], v178 offset:3072
	s_add_u32 s0, s70, 0xfff80080
	s_addc_u32 s1, s71, -1
	s_cmp_eq_u32 s76, 28
	s_cselect_b32 s13, s9, s1
	s_cselect_b32 s12, s61, s0
	s_cselect_b32 s1, s63, s21
	s_cselect_b32 s0, s75, s20
	v_lshl_add_u64 v[174:175], s[70:71], 0, v[166:167]
	s_add_i32 m0, s35, 0xc000
	ds_read_b128 v[198:201], v179
	ds_read_b128 v[202:205], v179 offset:1024
	ds_read_b128 v[206:209], v179 offset:2048
	ds_read_b128 v[210:213], v179 offset:3072
	ds_read_b128 v[214:217], v179 offset:4096
	ds_read_b128 v[218:221], v179 offset:5120
	ds_read_b128 v[222:225], v179 offset:6144
	ds_read_b128 v[226:229], v179 offset:7168
	global_load_lds_dwordx4 v[174:175], off
	v_lshl_add_u64 v[174:175], s[70:71], 0, v[168:169]
	s_add_i32 m0, s35, 0xe000
	s_nop 0
	global_load_lds_dwordx4 v[174:175], off
	s_waitcnt vmcnt(8)
	s_waitcnt lgkmcnt(0)
	s_barrier
	s_waitcnt lgkmcnt(0)
	v_mfma_f32_16x16x32_bf16 v[142:145], v[114:117], v[198:201], v[142:145]
	v_mfma_f32_16x16x32_bf16 v[138:141], v[122:125], v[198:201], v[138:141]
	v_mfma_f32_16x16x32_bf16 v[110:113], v[114:117], v[206:209], v[110:113]
	v_mfma_f32_16x16x32_bf16 v[106:109], v[122:125], v[206:209], v[106:109]
	v_mfma_f32_16x16x32_bf16 v[94:97], v[114:117], v[214:217], v[94:97]
	v_mfma_f32_16x16x32_bf16 v[90:93], v[122:125], v[214:217], v[90:93]
	v_mfma_f32_16x16x32_bf16 v[78:81], v[114:117], v[222:225], v[78:81]
	v_mfma_f32_16x16x32_bf16 v[74:77], v[122:125], v[222:225], v[74:77]
	v_mfma_f32_16x16x32_bf16 v[142:145], v[118:121], v[202:205], v[142:145]
	v_mfma_f32_16x16x32_bf16 v[138:141], v[126:129], v[202:205], v[138:141]
	v_mfma_f32_16x16x32_bf16 v[110:113], v[118:121], v[210:213], v[110:113]
	v_mfma_f32_16x16x32_bf16 v[106:109], v[126:129], v[210:213], v[106:109]
	v_mfma_f32_16x16x32_bf16 v[94:97], v[118:121], v[218:221], v[94:97]
	v_mfma_f32_16x16x32_bf16 v[90:93], v[126:129], v[218:221], v[90:93]
	v_mfma_f32_16x16x32_bf16 v[78:81], v[118:121], v[226:229], v[78:81]
	v_mfma_f32_16x16x32_bf16 v[74:77], v[126:129], v[226:229], v[74:77]
	v_mfma_f32_16x16x32_bf16 v[134:137], v[182:185], v[198:201], v[134:137]
	v_mfma_f32_16x16x32_bf16 v[130:133], v[190:193], v[198:201], v[130:133]
	v_mfma_f32_16x16x32_bf16 v[102:105], v[182:185], v[206:209], v[102:105]
	v_mfma_f32_16x16x32_bf16 v[98:101], v[190:193], v[206:209], v[98:101]
	v_mfma_f32_16x16x32_bf16 v[86:89], v[182:185], v[214:217], v[86:89]
	v_mfma_f32_16x16x32_bf16 v[82:85], v[190:193], v[214:217], v[82:85]
	v_mfma_f32_16x16x32_bf16 v[70:73], v[182:185], v[222:225], v[70:73]
	v_mfma_f32_16x16x32_bf16 v[66:69], v[190:193], v[222:225], v[66:69]
	v_mfma_f32_16x16x32_bf16 v[134:137], v[186:189], v[202:205], v[134:137]
	v_mfma_f32_16x16x32_bf16 v[130:133], v[194:197], v[202:205], v[130:133]
	v_mfma_f32_16x16x32_bf16 v[102:105], v[186:189], v[210:213], v[102:105]
	v_mfma_f32_16x16x32_bf16 v[98:101], v[194:197], v[210:213], v[98:101]
	v_mfma_f32_16x16x32_bf16 v[86:89], v[186:189], v[218:221], v[86:89]
	v_mfma_f32_16x16x32_bf16 v[82:85], v[194:197], v[218:221], v[82:85]
	v_mfma_f32_16x16x32_bf16 v[70:73], v[186:189], v[226:229], v[70:73]
	v_mfma_f32_16x16x32_bf16 v[66:69], v[194:197], v[226:229], v[66:69]
	s_barrier
	s_add_i32 s77, s72, s34
	v_lshl_add_u64 v[174:175], s[0:1], 0, v[148:149]
	s_mov_b32 m0, s77
	ds_read_b128 v[198:201], v179 offset:16384
	ds_read_b128 v[202:205], v179 offset:17408
	ds_read_b128 v[206:209], v179 offset:18432
	ds_read_b128 v[210:213], v179 offset:19456
	ds_read_b128 v[214:217], v179 offset:20480
	ds_read_b128 v[218:221], v179 offset:21504
	ds_read_b128 v[222:225], v179 offset:22528
	ds_read_b128 v[226:229], v179 offset:23552
	global_load_lds_dwordx4 v[174:175], off
	s_add_i32 m0, s77, 0x2000
	s_add_u32 s78, s0, 0x20000
	v_lshl_add_u64 v[230:231], s[0:1], 0, v[152:153]
	s_addc_u32 s79, s1, 0
	s_add_i32 s77, s73, s34
	global_load_lds_dwordx4 v[230:231], off
	v_lshl_add_u64 v[232:233], s[78:79], 0, v[148:149]
	s_mov_b32 m0, s77
	v_lshl_add_u64 v[234:235], s[12:13], 0, v[150:151]
	global_load_lds_dwordx4 v[232:233], off
	v_lshl_add_u64 v[232:233], s[78:79], 0, v[152:153]
	s_add_i32 m0, s77, 0x2000
	s_nop 0
	global_load_lds_dwordx4 v[232:233], off
	v_lshl_add_u64 v[232:233], s[12:13], 0, v[146:147]
	s_mov_b32 m0, s35
	s_nop 0
	global_load_lds_dwordx4 v[232:233], off
	s_mov_b32 m0, s36
	s_nop 0
	global_load_lds_dwordx4 v[234:235], off
	s_waitcnt vmcnt(8)
	s_waitcnt lgkmcnt(0)
	s_barrier
	s_waitcnt lgkmcnt(0)
	v_mfma_f32_16x16x32_bf16 v[62:65], v[114:117], v[198:201], v[62:65]
	v_mfma_f32_16x16x32_bf16 v[58:61], v[122:125], v[198:201], v[58:61]
	v_mfma_f32_16x16x32_bf16 v[46:49], v[114:117], v[206:209], v[46:49]
	v_mfma_f32_16x16x32_bf16 v[42:45], v[122:125], v[206:209], v[42:45]
	v_mfma_f32_16x16x32_bf16 v[30:33], v[114:117], v[214:217], v[30:33]
	v_mfma_f32_16x16x32_bf16 v[26:29], v[122:125], v[214:217], v[26:29]
	v_mfma_f32_16x16x32_bf16 v[14:17], v[114:117], v[222:225], v[14:17]
	v_mfma_f32_16x16x32_bf16 v[10:13], v[122:125], v[222:225], v[10:13]
	v_mfma_f32_16x16x32_bf16 v[62:65], v[118:121], v[202:205], v[62:65]
	v_mfma_f32_16x16x32_bf16 v[58:61], v[126:129], v[202:205], v[58:61]
	v_mfma_f32_16x16x32_bf16 v[46:49], v[118:121], v[210:213], v[46:49]
	v_mfma_f32_16x16x32_bf16 v[42:45], v[126:129], v[210:213], v[42:45]
	v_mfma_f32_16x16x32_bf16 v[30:33], v[118:121], v[218:221], v[30:33]
	v_mfma_f32_16x16x32_bf16 v[26:29], v[126:129], v[218:221], v[26:29]
	v_mfma_f32_16x16x32_bf16 v[14:17], v[118:121], v[226:229], v[14:17]
	v_mfma_f32_16x16x32_bf16 v[10:13], v[126:129], v[226:229], v[10:13]
	v_mfma_f32_16x16x32_bf16 v[54:57], v[182:185], v[198:201], v[54:57]
	v_mfma_f32_16x16x32_bf16 v[50:53], v[190:193], v[198:201], v[50:53]
	v_mfma_f32_16x16x32_bf16 v[38:41], v[182:185], v[206:209], v[38:41]
	v_mfma_f32_16x16x32_bf16 v[34:37], v[190:193], v[206:209], v[34:37]
	v_mfma_f32_16x16x32_bf16 v[22:25], v[182:185], v[214:217], v[22:25]
	v_mfma_f32_16x16x32_bf16 v[18:21], v[190:193], v[214:217], v[18:21]
	v_mfma_f32_16x16x32_bf16 v[6:9], v[182:185], v[222:225], v[6:9]
	v_mfma_f32_16x16x32_bf16 v[2:5], v[190:193], v[222:225], v[2:5]
	v_mfma_f32_16x16x32_bf16 v[54:57], v[186:189], v[202:205], v[54:57]
	v_mfma_f32_16x16x32_bf16 v[50:53], v[194:197], v[202:205], v[50:53]
	v_mfma_f32_16x16x32_bf16 v[38:41], v[186:189], v[210:213], v[38:41]
	v_mfma_f32_16x16x32_bf16 v[34:37], v[194:197], v[210:213], v[34:37]
	v_mfma_f32_16x16x32_bf16 v[22:25], v[186:189], v[218:221], v[22:25]
	v_mfma_f32_16x16x32_bf16 v[18:21], v[194:197], v[218:221], v[18:21]
	v_mfma_f32_16x16x32_bf16 v[6:9], v[186:189], v[226:229], v[6:9]
	v_mfma_f32_16x16x32_bf16 v[2:5], v[194:197], v[226:229], v[2:5]
	s_barrier
	s_add_i32 s77, 0, 0x18000
	s_add_i32 s78, 0, 0x1c000
	v_add_u32_e32 v126, s77, v159
	v_add_u32_e32 v154, s78, v159
	ds_read_b128 v[114:117], v126
	ds_read_b128 v[118:121], v126 offset:1024
	ds_read_b128 v[122:125], v126 offset:2048
	ds_read_b128 v[126:129], v126 offset:3072
	ds_read_b128 v[182:185], v154
	ds_read_b128 v[186:189], v154 offset:1024
	ds_read_b128 v[190:193], v154 offset:2048
	ds_read_b128 v[194:197], v154 offset:3072
	s_add_u32 s12, s12, 0x80000
	s_addc_u32 s13, s13, 0
	s_mov_b32 m0, s37
	v_lshl_add_u64 v[236:237], s[12:13], 0, v[146:147]
	ds_read_b128 v[198:201], v179 offset:32768
	ds_read_b128 v[202:205], v179 offset:33792
	ds_read_b128 v[206:209], v179 offset:34816
	ds_read_b128 v[210:213], v179 offset:35840
	ds_read_b128 v[214:217], v179 offset:36864
	ds_read_b128 v[218:221], v179 offset:37888
	ds_read_b128 v[222:225], v179 offset:38912
	ds_read_b128 v[226:229], v179 offset:39936
	global_load_lds_dwordx4 v[236:237], off
	v_lshl_add_u64 v[236:237], s[12:13], 0, v[150:151]
	s_mov_b32 m0, s38
	s_nop 0
	global_load_lds_dwordx4 v[236:237], off
	s_waitcnt vmcnt(8)
	s_waitcnt lgkmcnt(0)
	s_barrier
	s_waitcnt lgkmcnt(0)
	v_mfma_f32_16x16x32_bf16 v[142:145], v[114:117], v[198:201], v[142:145]
	v_mfma_f32_16x16x32_bf16 v[138:141], v[122:125], v[198:201], v[138:141]
	v_mfma_f32_16x16x32_bf16 v[110:113], v[114:117], v[206:209], v[110:113]
	v_mfma_f32_16x16x32_bf16 v[106:109], v[122:125], v[206:209], v[106:109]
	v_mfma_f32_16x16x32_bf16 v[94:97], v[114:117], v[214:217], v[94:97]
	v_mfma_f32_16x16x32_bf16 v[90:93], v[122:125], v[214:217], v[90:93]
	v_mfma_f32_16x16x32_bf16 v[78:81], v[114:117], v[222:225], v[78:81]
	v_mfma_f32_16x16x32_bf16 v[74:77], v[122:125], v[222:225], v[74:77]
	v_mfma_f32_16x16x32_bf16 v[142:145], v[118:121], v[202:205], v[142:145]
	v_mfma_f32_16x16x32_bf16 v[138:141], v[126:129], v[202:205], v[138:141]
	v_mfma_f32_16x16x32_bf16 v[110:113], v[118:121], v[210:213], v[110:113]
	v_mfma_f32_16x16x32_bf16 v[106:109], v[126:129], v[210:213], v[106:109]
	v_mfma_f32_16x16x32_bf16 v[94:97], v[118:121], v[218:221], v[94:97]
	v_mfma_f32_16x16x32_bf16 v[90:93], v[126:129], v[218:221], v[90:93]
	v_mfma_f32_16x16x32_bf16 v[78:81], v[118:121], v[226:229], v[78:81]
	v_mfma_f32_16x16x32_bf16 v[74:77], v[126:129], v[226:229], v[74:77]
	v_mfma_f32_16x16x32_bf16 v[134:137], v[182:185], v[198:201], v[134:137]
	v_mfma_f32_16x16x32_bf16 v[130:133], v[190:193], v[198:201], v[130:133]
	v_mfma_f32_16x16x32_bf16 v[102:105], v[182:185], v[206:209], v[102:105]
	v_mfma_f32_16x16x32_bf16 v[98:101], v[190:193], v[206:209], v[98:101]
	v_mfma_f32_16x16x32_bf16 v[86:89], v[182:185], v[214:217], v[86:89]
	v_mfma_f32_16x16x32_bf16 v[82:85], v[190:193], v[214:217], v[82:85]
	v_mfma_f32_16x16x32_bf16 v[70:73], v[182:185], v[222:225], v[70:73]
	v_mfma_f32_16x16x32_bf16 v[66:69], v[190:193], v[222:225], v[66:69]
	v_mfma_f32_16x16x32_bf16 v[134:137], v[186:189], v[202:205], v[134:137]
	v_mfma_f32_16x16x32_bf16 v[130:133], v[194:197], v[202:205], v[130:133]
	v_mfma_f32_16x16x32_bf16 v[102:105], v[186:189], v[210:213], v[102:105]
	v_mfma_f32_16x16x32_bf16 v[98:101], v[194:197], v[210:213], v[98:101]
	v_mfma_f32_16x16x32_bf16 v[86:89], v[186:189], v[218:221], v[86:89]
	v_mfma_f32_16x16x32_bf16 v[82:85], v[194:197], v[218:221], v[82:85]
	v_mfma_f32_16x16x32_bf16 v[70:73], v[186:189], v[226:229], v[70:73]
	v_mfma_f32_16x16x32_bf16 v[66:69], v[194:197], v[226:229], v[66:69]
	s_barrier
	s_add_i32 s12, s77, s34
	v_lshl_add_u64 v[174:175], v[174:175], 0, s[52:53]
	s_mov_b32 m0, s12
	ds_read_b128 v[198:201], v179 offset:49152
	ds_read_b128 v[202:205], v179 offset:50176
	ds_read_b128 v[206:209], v179 offset:51200
	ds_read_b128 v[210:213], v179 offset:52224
	ds_read_b128 v[214:217], v179 offset:53248
	ds_read_b128 v[218:221], v179 offset:54272
	ds_read_b128 v[222:225], v179 offset:55296
	ds_read_b128 v[226:229], v179 offset:56320
	global_load_lds_dwordx4 v[174:175], off
	s_add_i32 m0, s12, 0x2000
	s_add_u32 s0, s0, 0x20080
	v_lshl_add_u64 v[174:175], v[230:231], 0, s[52:53]
	s_addc_u32 s1, s1, 0
	s_add_i32 s12, s78, s34
	global_load_lds_dwordx4 v[174:175], off
	v_lshl_add_u64 v[174:175], s[0:1], 0, v[148:149]
	s_mov_b32 m0, s12
	s_nop 0
	global_load_lds_dwordx4 v[174:175], off
	v_lshl_add_u64 v[174:175], s[0:1], 0, v[152:153]
	s_add_i32 m0, s12, 0x2000
	s_nop 0
	global_load_lds_dwordx4 v[174:175], off
	v_lshl_add_u64 v[174:175], v[232:233], 0, s[52:53]
	s_mov_b32 m0, s44
	s_nop 0
	global_load_lds_dwordx4 v[174:175], off
	v_lshl_add_u64 v[174:175], v[234:235], 0, s[52:53]
	s_mov_b32 m0, s45
	s_nop 0
	global_load_lds_dwordx4 v[174:175], off
	s_waitcnt vmcnt(8)
	s_waitcnt lgkmcnt(0)
	s_barrier
	s_waitcnt lgkmcnt(0)
	v_mfma_f32_16x16x32_bf16 v[62:65], v[114:117], v[198:201], v[62:65]
	v_mfma_f32_16x16x32_bf16 v[58:61], v[122:125], v[198:201], v[58:61]
	v_mfma_f32_16x16x32_bf16 v[46:49], v[114:117], v[206:209], v[46:49]
	v_mfma_f32_16x16x32_bf16 v[42:45], v[122:125], v[206:209], v[42:45]
	v_mfma_f32_16x16x32_bf16 v[30:33], v[114:117], v[214:217], v[30:33]
	v_mfma_f32_16x16x32_bf16 v[26:29], v[122:125], v[214:217], v[26:29]
	v_mfma_f32_16x16x32_bf16 v[14:17], v[114:117], v[222:225], v[14:17]
	v_mfma_f32_16x16x32_bf16 v[10:13], v[122:125], v[222:225], v[10:13]
	v_mfma_f32_16x16x32_bf16 v[62:65], v[118:121], v[202:205], v[62:65]
	v_mfma_f32_16x16x32_bf16 v[58:61], v[126:129], v[202:205], v[58:61]
	v_mfma_f32_16x16x32_bf16 v[46:49], v[118:121], v[210:213], v[46:49]
	v_mfma_f32_16x16x32_bf16 v[42:45], v[126:129], v[210:213], v[42:45]
	v_mfma_f32_16x16x32_bf16 v[30:33], v[118:121], v[218:221], v[30:33]
	v_mfma_f32_16x16x32_bf16 v[26:29], v[126:129], v[218:221], v[26:29]
	v_mfma_f32_16x16x32_bf16 v[14:17], v[118:121], v[226:229], v[14:17]
	v_mfma_f32_16x16x32_bf16 v[10:13], v[126:129], v[226:229], v[10:13]
	v_mfma_f32_16x16x32_bf16 v[54:57], v[182:185], v[198:201], v[54:57]
	v_mfma_f32_16x16x32_bf16 v[50:53], v[190:193], v[198:201], v[50:53]
	v_mfma_f32_16x16x32_bf16 v[38:41], v[182:185], v[206:209], v[38:41]
	v_mfma_f32_16x16x32_bf16 v[34:37], v[190:193], v[206:209], v[34:37]
	v_mfma_f32_16x16x32_bf16 v[22:25], v[182:185], v[214:217], v[22:25]
	v_mfma_f32_16x16x32_bf16 v[18:21], v[190:193], v[214:217], v[18:21]
	v_mfma_f32_16x16x32_bf16 v[6:9], v[182:185], v[222:225], v[6:9]
	v_mfma_f32_16x16x32_bf16 v[2:5], v[190:193], v[222:225], v[2:5]
	v_mfma_f32_16x16x32_bf16 v[54:57], v[186:189], v[202:205], v[54:57]
	v_mfma_f32_16x16x32_bf16 v[50:53], v[194:197], v[202:205], v[50:53]
	v_mfma_f32_16x16x32_bf16 v[38:41], v[186:189], v[210:213], v[38:41]
	v_mfma_f32_16x16x32_bf16 v[34:37], v[194:197], v[210:213], v[34:37]
	v_mfma_f32_16x16x32_bf16 v[22:25], v[186:189], v[218:221], v[22:25]
	v_mfma_f32_16x16x32_bf16 v[18:21], v[194:197], v[218:221], v[18:21]
	v_mfma_f32_16x16x32_bf16 v[6:9], v[186:189], v[226:229], v[6:9]
	v_mfma_f32_16x16x32_bf16 v[2:5], v[194:197], v[226:229], v[2:5]
	s_barrier
	s_add_i32 s76, s76, 2
	s_add_u32 s70, s70, 0x100
	s_addc_u32 s71, s71, 0
	s_add_u32 s20, s20, 0x100
	s_addc_u32 s21, s21, 0
	s_cmp_gt_u32 s76, 29
	s_cbranch_scc0 .LBB0_165
	s_setprio 0
	s_and_b64 vcc, exec, s[56:57]
	s_cbranch_vccz .LBB0_168
	s_barrier

.LBB0_496:
	s_mov_b32 s47, s61
	s_mov_b32 s62, s61
	s_add_i32 s61, s46, s10
	s_mov_b64 s[8:9], s[14:15]
	s_and_b64 s[14:15], s[44:45], exec
	s_cselect_b32 s14, s61, s47
	s_ashr_i32 s15, s14, 31
	s_lshl_b64 s[14:15], s[14:15], 20
	s_add_u32 s14, s18, s14
	s_addc_u32 s15, s19, s15
	s_and_b64 s[46:47], s[44:45], exec
	s_cselect_b32 s63, s15, s9
	s_cselect_b32 s64, s14, s8
	s_add_u32 s8, s8, 0x80080
	v_mov_b32_e32 v60, 0
	s_addc_u32 s9, s9, 0
	s_mov_b32 s65, -2
	s_mov_b64 s[46:47], s[26:27]
	v_mov_b32_e32 v61, v60
	v_mov_b32_e32 v62, v60
	v_mov_b32_e32 v63, v60
	v_mov_b32_e32 v56, v60
	v_mov_b32_e32 v57, v60
	v_mov_b32_e32 v58, v60
	v_mov_b32_e32 v59, v60
	v_mov_b32_e32 v36, v60
	v_mov_b32_e32 v37, v60
	v_mov_b32_e32 v38, v60
	v_mov_b32_e32 v39, v60
	v_mov_b32_e32 v32, v60
	v_mov_b32_e32 v33, v60
	v_mov_b32_e32 v34, v60
	v_mov_b32_e32 v35, v60
	v_mov_b32_e32 v16, v60
	v_mov_b32_e32 v17, v60
	v_mov_b32_e32 v18, v60
	v_mov_b32_e32 v19, v60
	v_mov_b32_e32 v8, v60
	v_mov_b32_e32 v9, v60
	v_mov_b32_e32 v10, v60
	v_mov_b32_e32 v11, v60
	v_mov_b32_e32 v4, v60
	v_mov_b32_e32 v5, v60
	v_mov_b32_e32 v6, v60
	v_mov_b32_e32 v7, v60
	v_mov_b32_e32 v0, v60
	v_mov_b32_e32 v1, v60
	v_mov_b32_e32 v2, v60
	v_mov_b32_e32 v3, v60
	v_mov_b32_e32 v52, v60
	v_mov_b32_e32 v53, v60
	v_mov_b32_e32 v54, v60
	v_mov_b32_e32 v55, v60
	v_mov_b32_e32 v48, v60
	v_mov_b32_e32 v49, v60
	v_mov_b32_e32 v50, v60
	v_mov_b32_e32 v51, v60
	v_mov_b32_e32 v44, v60
	v_mov_b32_e32 v45, v60
	v_mov_b32_e32 v46, v60
	v_mov_b32_e32 v47, v60
	v_mov_b32_e32 v40, v60
	v_mov_b32_e32 v41, v60
	v_mov_b32_e32 v42, v60
	v_mov_b32_e32 v43, v60
	v_mov_b32_e32 v28, v60
	v_mov_b32_e32 v29, v60
	v_mov_b32_e32 v30, v60
	v_mov_b32_e32 v31, v60
	v_mov_b32_e32 v24, v60
	v_mov_b32_e32 v25, v60
	v_mov_b32_e32 v26, v60
	v_mov_b32_e32 v27, v60
	v_mov_b32_e32 v20, v60
	v_mov_b32_e32 v21, v60
	v_mov_b32_e32 v22, v60
	v_mov_b32_e32 v23, v60
	v_mov_b32_e32 v12, v60
	v_mov_b32_e32 v13, v60
	v_mov_b32_e32 v14, v60
	v_mov_b32_e32 v15, v60
	v_mov_b32_e32 v88, v60
	v_mov_b32_e32 v89, v60
	v_mov_b32_e32 v90, v60
	v_mov_b32_e32 v91, v60
	v_mov_b32_e32 v80, v60
	v_mov_b32_e32 v81, v60
	v_mov_b32_e32 v82, v60
	v_mov_b32_e32 v83, v60
	v_mov_b32_e32 v104, v60
	v_mov_b32_e32 v105, v60
	v_mov_b32_e32 v106, v60
	v_mov_b32_e32 v107, v60
	v_mov_b32_e32 v84, v60
	v_mov_b32_e32 v85, v60
	v_mov_b32_e32 v86, v60
	v_mov_b32_e32 v87, v60
	v_mov_b32_e32 v68, v60
	v_mov_b32_e32 v69, v60
	v_mov_b32_e32 v70, v60
	v_mov_b32_e32 v71, v60
	v_mov_b32_e32 v64, v60
	v_mov_b32_e32 v65, v60
	v_mov_b32_e32 v66, v60
	v_mov_b32_e32 v67, v60
	v_mov_b32_e32 v72, v60
	v_mov_b32_e32 v73, v60
	v_mov_b32_e32 v74, v60
	v_mov_b32_e32 v75, v60
	v_mov_b32_e32 v92, v60
	v_mov_b32_e32 v93, v60
	v_mov_b32_e32 v94, v60
	v_mov_b32_e32 v95, v60
	v_mov_b32_e32 v116, v60
	v_mov_b32_e32 v117, v60
	v_mov_b32_e32 v118, v60
	v_mov_b32_e32 v119, v60
	v_mov_b32_e32 v112, v60
	v_mov_b32_e32 v113, v60
	v_mov_b32_e32 v114, v60
	v_mov_b32_e32 v115, v60
	v_mov_b32_e32 v120, v60
	v_mov_b32_e32 v121, v60
	v_mov_b32_e32 v122, v60
	v_mov_b32_e32 v123, v60
	v_mov_b32_e32 v124, v60
	v_mov_b32_e32 v125, v60
	v_mov_b32_e32 v126, v60
	v_mov_b32_e32 v127, v60
	v_mov_b32_e32 v76, v60
	v_mov_b32_e32 v77, v60
	v_mov_b32_e32 v78, v60
	v_mov_b32_e32 v79, v60
	v_mov_b32_e32 v128, v60
	v_mov_b32_e32 v129, v60
	v_mov_b32_e32 v130, v60
	v_mov_b32_e32 v131, v60
	v_mov_b32_e32 v96, v60
	v_mov_b32_e32 v97, v60
	v_mov_b32_e32 v98, v60
	v_mov_b32_e32 v99, v60
	v_mov_b32_e32 v100, v60
	v_mov_b32_e32 v101, v60
	v_mov_b32_e32 v102, v60
	v_mov_b32_e32 v103, v60
	s_cmp_eq_u64 s[36:37], 0
	s_cbranch_scc0 .Lprio_p4
	s_setprio 1
.Lprio_p4:
.LBB0_497:
	ds_read_b128 v[108:111], v215
	ds_read_b128 v[132:135], v215 offset:1024
	ds_read_b128 v[136:139], v215 offset:2048
	ds_read_b128 v[140:143], v215 offset:3072
	ds_read_b128 v[144:147], v220
	ds_read_b128 v[148:151], v220 offset:1024
	ds_read_b128 v[152:155], v220 offset:2048
	ds_read_b128 v[156:159], v220 offset:3072
	s_add_u32 s48, s8, 0xfff80080
	s_addc_u32 s49, s9, -1
	s_cmp_eq_u32 s65, 28
	s_cselect_b32 s51, s63, s49
	s_cselect_b32 s50, s64, s48
	s_cselect_b32 s49, s13, s47
	s_cselect_b32 s48, s12, s46
	v_lshl_add_u64 v[244:245], s[8:9], 0, v[178:179]
	s_add_i32 m0, s11, 0xc000
	ds_read_b128 v[184:187], v216
	ds_read_b128 v[188:191], v216 offset:1024
	ds_read_b128 v[192:195], v216 offset:2048
	ds_read_b128 v[224:227], v216 offset:3072
	ds_read_b128 v[228:231], v216 offset:4096
	ds_read_b128 v[232:235], v216 offset:5120
	ds_read_b128 v[236:239], v216 offset:6144
	ds_read_b128 v[240:243], v216 offset:7168
	global_load_lds_dwordx4 v[244:245], off
	v_lshl_add_u64 v[244:245], s[8:9], 0, v[180:181]
	s_add_i32 m0, s11, 0xe000
	s_nop 0
	global_load_lds_dwordx4 v[244:245], off
	s_waitcnt vmcnt(8)
	s_waitcnt lgkmcnt(0)
	s_barrier
	s_waitcnt lgkmcnt(0)
	v_mfma_f32_16x16x32_bf16 v[100:103], v[108:111], v[184:187], v[100:103]
	v_mfma_f32_16x16x32_bf16 v[96:99], v[136:139], v[184:187], v[96:99]
	v_mfma_f32_16x16x32_bf16 v[128:131], v[108:111], v[192:195], v[128:131]
	v_mfma_f32_16x16x32_bf16 v[76:79], v[136:139], v[192:195], v[76:79]
	v_mfma_f32_16x16x32_bf16 v[124:127], v[108:111], v[228:231], v[124:127]
	v_mfma_f32_16x16x32_bf16 v[120:123], v[136:139], v[228:231], v[120:123]
	v_mfma_f32_16x16x32_bf16 v[112:115], v[108:111], v[236:239], v[112:115]
	v_mfma_f32_16x16x32_bf16 v[116:119], v[136:139], v[236:239], v[116:119]
	v_mfma_f32_16x16x32_bf16 v[100:103], v[132:135], v[188:191], v[100:103]
	v_mfma_f32_16x16x32_bf16 v[96:99], v[140:143], v[188:191], v[96:99]
	v_mfma_f32_16x16x32_bf16 v[128:131], v[132:135], v[224:227], v[128:131]
	v_mfma_f32_16x16x32_bf16 v[76:79], v[140:143], v[224:227], v[76:79]
	v_mfma_f32_16x16x32_bf16 v[124:127], v[132:135], v[232:235], v[124:127]
	v_mfma_f32_16x16x32_bf16 v[120:123], v[140:143], v[232:235], v[120:123]
	v_mfma_f32_16x16x32_bf16 v[112:115], v[132:135], v[240:243], v[112:115]
	v_mfma_f32_16x16x32_bf16 v[116:119], v[140:143], v[240:243], v[116:119]
	v_mfma_f32_16x16x32_bf16 v[92:95], v[144:147], v[184:187], v[92:95]
	v_mfma_f32_16x16x32_bf16 v[72:75], v[152:155], v[184:187], v[72:75]
	v_mfma_f32_16x16x32_bf16 v[64:67], v[144:147], v[192:195], v[64:67]
	v_mfma_f32_16x16x32_bf16 v[68:71], v[152:155], v[192:195], v[68:71]
	v_mfma_f32_16x16x32_bf16 v[84:87], v[144:147], v[228:231], v[84:87]
	v_mfma_f32_16x16x32_bf16 v[104:107], v[152:155], v[228:231], v[104:107]
	v_mfma_f32_16x16x32_bf16 v[80:83], v[144:147], v[236:239], v[80:83]
	v_mfma_f32_16x16x32_bf16 v[88:91], v[152:155], v[236:239], v[88:91]
	v_mfma_f32_16x16x32_bf16 v[92:95], v[148:151], v[188:191], v[92:95]
	v_mfma_f32_16x16x32_bf16 v[72:75], v[156:159], v[188:191], v[72:75]
	v_mfma_f32_16x16x32_bf16 v[64:67], v[148:151], v[224:227], v[64:67]
	v_mfma_f32_16x16x32_bf16 v[68:71], v[156:159], v[224:227], v[68:71]
	v_mfma_f32_16x16x32_bf16 v[84:87], v[148:151], v[232:235], v[84:87]
	v_mfma_f32_16x16x32_bf16 v[104:107], v[156:159], v[232:235], v[104:107]
	v_mfma_f32_16x16x32_bf16 v[80:83], v[148:151], v[240:243], v[80:83]
	v_mfma_f32_16x16x32_bf16 v[88:91], v[156:159], v[240:243], v[88:91]
	s_barrier
	s_add_i32 s66, s29, s52
	v_lshl_add_u64 v[244:245], s[48:49], 0, v[162:163]
	s_mov_b32 m0, s66
	ds_read_b128 v[184:187], v216 offset:16384
	ds_read_b128 v[188:191], v216 offset:17408
	ds_read_b128 v[192:195], v216 offset:18432
	ds_read_b128 v[224:227], v216 offset:19456
	ds_read_b128 v[228:231], v216 offset:20480
	ds_read_b128 v[232:235], v216 offset:21504
	ds_read_b128 v[236:239], v216 offset:22528
	ds_read_b128 v[240:243], v216 offset:23552
	global_load_lds_dwordx4 v[244:245], off
	s_add_i32 m0, s66, 0x2000
	s_add_u32 s66, s48, 0x20000
	v_lshl_add_u64 v[246:247], s[48:49], 0, v[166:167]
	s_addc_u32 s67, s49, 0
	s_add_i32 s68, s59, s52
	global_load_lds_dwordx4 v[246:247], off
	v_lshl_add_u64 v[248:249], s[66:67], 0, v[162:163]
	s_mov_b32 m0, s68
	v_lshl_add_u64 v[250:251], s[50:51], 0, v[164:165]
	global_load_lds_dwordx4 v[248:249], off
	v_lshl_add_u64 v[248:249], s[66:67], 0, v[166:167]
	s_add_i32 m0, s68, 0x2000
	s_nop 0
	global_load_lds_dwordx4 v[248:249], off
	v_lshl_add_u64 v[248:249], s[50:51], 0, v[160:161]
	s_mov_b32 m0, s11
	s_nop 0
	global_load_lds_dwordx4 v[248:249], off
	s_mov_b32 m0, s33
	s_nop 0
	global_load_lds_dwordx4 v[250:251], off
	s_waitcnt vmcnt(8)
	s_waitcnt lgkmcnt(0)
	s_barrier
	s_waitcnt lgkmcnt(0)
	v_mfma_f32_16x16x32_bf16 v[12:15], v[108:111], v[184:187], v[12:15]
	v_mfma_f32_16x16x32_bf16 v[20:23], v[136:139], v[184:187], v[20:23]
	v_mfma_f32_16x16x32_bf16 v[24:27], v[108:111], v[192:195], v[24:27]
	v_mfma_f32_16x16x32_bf16 v[28:31], v[136:139], v[192:195], v[28:31]
	v_mfma_f32_16x16x32_bf16 v[40:43], v[108:111], v[228:231], v[40:43]
	v_mfma_f32_16x16x32_bf16 v[44:47], v[136:139], v[228:231], v[44:47]
	v_mfma_f32_16x16x32_bf16 v[48:51], v[108:111], v[236:239], v[48:51]
	v_mfma_f32_16x16x32_bf16 v[52:55], v[136:139], v[236:239], v[52:55]
	v_mfma_f32_16x16x32_bf16 v[12:15], v[132:135], v[188:191], v[12:15]
	v_mfma_f32_16x16x32_bf16 v[20:23], v[140:143], v[188:191], v[20:23]
	v_mfma_f32_16x16x32_bf16 v[24:27], v[132:135], v[224:227], v[24:27]
	v_mfma_f32_16x16x32_bf16 v[28:31], v[140:143], v[224:227], v[28:31]
	v_mfma_f32_16x16x32_bf16 v[40:43], v[132:135], v[232:235], v[40:43]
	v_mfma_f32_16x16x32_bf16 v[44:47], v[140:143], v[232:235], v[44:47]
	v_mfma_f32_16x16x32_bf16 v[48:51], v[132:135], v[240:243], v[48:51]
	v_mfma_f32_16x16x32_bf16 v[52:55], v[140:143], v[240:243], v[52:55]
	v_mfma_f32_16x16x32_bf16 v[0:3], v[144:147], v[184:187], v[0:3]
	v_mfma_f32_16x16x32_bf16 v[4:7], v[152:155], v[184:187], v[4:7]
	v_mfma_f32_16x16x32_bf16 v[8:11], v[144:147], v[192:195], v[8:11]
	v_mfma_f32_16x16x32_bf16 v[16:19], v[152:155], v[192:195], v[16:19]
	v_mfma_f32_16x16x32_bf16 v[32:35], v[144:147], v[228:231], v[32:35]
	v_mfma_f32_16x16x32_bf16 v[36:39], v[152:155], v[228:231], v[36:39]
	v_mfma_f32_16x16x32_bf16 v[56:59], v[144:147], v[236:239], v[56:59]
	v_mfma_f32_16x16x32_bf16 v[60:63], v[152:155], v[236:239], v[60:63]
	v_mfma_f32_16x16x32_bf16 v[0:3], v[148:151], v[188:191], v[0:3]
	v_mfma_f32_16x16x32_bf16 v[4:7], v[156:159], v[188:191], v[4:7]
	v_mfma_f32_16x16x32_bf16 v[8:11], v[148:151], v[224:227], v[8:11]
	v_mfma_f32_16x16x32_bf16 v[16:19], v[156:159], v[224:227], v[16:19]
	v_mfma_f32_16x16x32_bf16 v[32:35], v[148:151], v[232:235], v[32:35]
	v_mfma_f32_16x16x32_bf16 v[36:39], v[156:159], v[232:235], v[36:39]
	v_mfma_f32_16x16x32_bf16 v[56:59], v[148:151], v[240:243], v[56:59]
	v_mfma_f32_16x16x32_bf16 v[60:63], v[156:159], v[240:243], v[60:63]
	s_barrier
	s_add_i32 s66, 0, 0x18000
	s_add_i32 s67, 0, 0x1c000
	v_add_u32_e32 v140, s66, v197
	v_add_u32_e32 v156, s67, v197
	ds_read_b128 v[108:111], v140
	ds_read_b128 v[132:135], v140 offset:1024
	ds_read_b128 v[136:139], v140 offset:2048
	ds_read_b128 v[140:143], v140 offset:3072
	ds_read_b128 v[144:147], v156
	ds_read_b128 v[148:151], v156 offset:1024
	ds_read_b128 v[152:155], v156 offset:2048
	ds_read_b128 v[156:159], v156 offset:3072
	s_add_u32 s50, s50, 0x80000
	s_addc_u32 s51, s51, 0
	s_mov_b32 m0, s53
	v_lshl_add_u64 v[252:253], s[50:51], 0, v[160:161]
	ds_read_b128 v[184:187], v216 offset:32768
	ds_read_b128 v[188:191], v216 offset:33792
	ds_read_b128 v[192:195], v216 offset:34816
	ds_read_b128 v[224:227], v216 offset:35840
	ds_read_b128 v[228:231], v216 offset:36864
	ds_read_b128 v[232:235], v216 offset:37888
	ds_read_b128 v[236:239], v216 offset:38912
	ds_read_b128 v[240:243], v216 offset:39936
	global_load_lds_dwordx4 v[252:253], off
	v_lshl_add_u64 v[252:253], s[50:51], 0, v[164:165]
	s_mov_b32 m0, s54
	s_nop 0
	global_load_lds_dwordx4 v[252:253], off
	s_waitcnt vmcnt(8)
	s_waitcnt lgkmcnt(0)
	s_barrier
	s_waitcnt lgkmcnt(0)
	v_mfma_f32_16x16x32_bf16 v[100:103], v[108:111], v[184:187], v[100:103]
	v_mfma_f32_16x16x32_bf16 v[96:99], v[136:139], v[184:187], v[96:99]
	v_mfma_f32_16x16x32_bf16 v[128:131], v[108:111], v[192:195], v[128:131]
	v_mfma_f32_16x16x32_bf16 v[76:79], v[136:139], v[192:195], v[76:79]
	v_mfma_f32_16x16x32_bf16 v[124:127], v[108:111], v[228:231], v[124:127]
	v_mfma_f32_16x16x32_bf16 v[120:123], v[136:139], v[228:231], v[120:123]
	v_mfma_f32_16x16x32_bf16 v[112:115], v[108:111], v[236:239], v[112:115]
	v_mfma_f32_16x16x32_bf16 v[116:119], v[136:139], v[236:239], v[116:119]
	v_mfma_f32_16x16x32_bf16 v[100:103], v[132:135], v[188:191], v[100:103]
	v_mfma_f32_16x16x32_bf16 v[96:99], v[140:143], v[188:191], v[96:99]
	v_mfma_f32_16x16x32_bf16 v[128:131], v[132:135], v[224:227], v[128:131]
	v_mfma_f32_16x16x32_bf16 v[76:79], v[140:143], v[224:227], v[76:79]
	v_mfma_f32_16x16x32_bf16 v[124:127], v[132:135], v[232:235], v[124:127]
	v_mfma_f32_16x16x32_bf16 v[120:123], v[140:143], v[232:235], v[120:123]
	v_mfma_f32_16x16x32_bf16 v[112:115], v[132:135], v[240:243], v[112:115]
	v_mfma_f32_16x16x32_bf16 v[116:119], v[140:143], v[240:243], v[116:119]
	v_mfma_f32_16x16x32_bf16 v[92:95], v[144:147], v[184:187], v[92:95]
	v_mfma_f32_16x16x32_bf16 v[72:75], v[152:155], v[184:187], v[72:75]
	v_mfma_f32_16x16x32_bf16 v[64:67], v[144:147], v[192:195], v[64:67]
	v_mfma_f32_16x16x32_bf16 v[68:71], v[152:155], v[192:195], v[68:71]
	v_mfma_f32_16x16x32_bf16 v[84:87], v[144:147], v[228:231], v[84:87]
	v_mfma_f32_16x16x32_bf16 v[104:107], v[152:155], v[228:231], v[104:107]
	v_mfma_f32_16x16x32_bf16 v[80:83], v[144:147], v[236:239], v[80:83]
	v_mfma_f32_16x16x32_bf16 v[88:91], v[152:155], v[236:239], v[88:91]
	v_mfma_f32_16x16x32_bf16 v[92:95], v[148:151], v[188:191], v[92:95]
	v_mfma_f32_16x16x32_bf16 v[72:75], v[156:159], v[188:191], v[72:75]
	v_mfma_f32_16x16x32_bf16 v[64:67], v[148:151], v[224:227], v[64:67]
	v_mfma_f32_16x16x32_bf16 v[68:71], v[156:159], v[224:227], v[68:71]
	v_mfma_f32_16x16x32_bf16 v[84:87], v[148:151], v[232:235], v[84:87]
	v_mfma_f32_16x16x32_bf16 v[104:107], v[156:159], v[232:235], v[104:107]
	v_mfma_f32_16x16x32_bf16 v[80:83], v[148:151], v[240:243], v[80:83]
	v_mfma_f32_16x16x32_bf16 v[88:91], v[156:159], v[240:243], v[88:91]
	s_barrier
	s_add_i32 s50, s66, s52
	v_lshl_add_u64 v[244:245], v[244:245], 0, s[24:25]
	s_mov_b32 m0, s50
	ds_read_b128 v[184:187], v216 offset:49152
	ds_read_b128 v[188:191], v216 offset:50176
	ds_read_b128 v[192:195], v216 offset:51200
	ds_read_b128 v[224:227], v216 offset:52224
	ds_read_b128 v[228:231], v216 offset:53248
	ds_read_b128 v[232:235], v216 offset:54272
	ds_read_b128 v[236:239], v216 offset:55296
	ds_read_b128 v[240:243], v216 offset:56320
	global_load_lds_dwordx4 v[244:245], off
	s_add_i32 m0, s50, 0x2000
	s_add_u32 s48, s48, 0x20080
	v_lshl_add_u64 v[244:245], v[246:247], 0, s[24:25]
	s_addc_u32 s49, s49, 0
	s_add_i32 s50, s67, s52
	global_load_lds_dwordx4 v[244:245], off
	v_lshl_add_u64 v[244:245], s[48:49], 0, v[162:163]
	s_mov_b32 m0, s50
	s_nop 0
	global_load_lds_dwordx4 v[244:245], off
	v_lshl_add_u64 v[244:245], s[48:49], 0, v[166:167]
	s_add_i32 m0, s50, 0x2000
	s_nop 0
	global_load_lds_dwordx4 v[244:245], off
	v_lshl_add_u64 v[244:245], v[248:249], 0, s[24:25]
	s_mov_b32 m0, s57
	s_nop 0
	global_load_lds_dwordx4 v[244:245], off
	v_lshl_add_u64 v[244:245], v[250:251], 0, s[24:25]
	s_mov_b32 m0, s58
	s_nop 0
	global_load_lds_dwordx4 v[244:245], off
	s_waitcnt vmcnt(8)
	s_waitcnt lgkmcnt(0)
	s_barrier
	s_waitcnt lgkmcnt(0)
	v_mfma_f32_16x16x32_bf16 v[12:15], v[108:111], v[184:187], v[12:15]
	v_mfma_f32_16x16x32_bf16 v[20:23], v[136:139], v[184:187], v[20:23]
	v_mfma_f32_16x16x32_bf16 v[24:27], v[108:111], v[192:195], v[24:27]
	v_mfma_f32_16x16x32_bf16 v[28:31], v[136:139], v[192:195], v[28:31]
	v_mfma_f32_16x16x32_bf16 v[40:43], v[108:111], v[228:231], v[40:43]
	v_mfma_f32_16x16x32_bf16 v[44:47], v[136:139], v[228:231], v[44:47]
	v_mfma_f32_16x16x32_bf16 v[48:51], v[108:111], v[236:239], v[48:51]
	v_mfma_f32_16x16x32_bf16 v[52:55], v[136:139], v[236:239], v[52:55]
	v_mfma_f32_16x16x32_bf16 v[12:15], v[132:135], v[188:191], v[12:15]
	v_mfma_f32_16x16x32_bf16 v[20:23], v[140:143], v[188:191], v[20:23]
	v_mfma_f32_16x16x32_bf16 v[24:27], v[132:135], v[224:227], v[24:27]
	v_mfma_f32_16x16x32_bf16 v[28:31], v[140:143], v[224:227], v[28:31]
	v_mfma_f32_16x16x32_bf16 v[40:43], v[132:135], v[232:235], v[40:43]
	v_mfma_f32_16x16x32_bf16 v[44:47], v[140:143], v[232:235], v[44:47]
	v_mfma_f32_16x16x32_bf16 v[48:51], v[132:135], v[240:243], v[48:51]
	v_mfma_f32_16x16x32_bf16 v[52:55], v[140:143], v[240:243], v[52:55]
	v_mfma_f32_16x16x32_bf16 v[0:3], v[144:147], v[184:187], v[0:3]
	v_mfma_f32_16x16x32_bf16 v[4:7], v[152:155], v[184:187], v[4:7]
	v_mfma_f32_16x16x32_bf16 v[8:11], v[144:147], v[192:195], v[8:11]
	v_mfma_f32_16x16x32_bf16 v[16:19], v[152:155], v[192:195], v[16:19]
	v_mfma_f32_16x16x32_bf16 v[32:35], v[144:147], v[228:231], v[32:35]
	v_mfma_f32_16x16x32_bf16 v[36:39], v[152:155], v[228:231], v[36:39]
	v_mfma_f32_16x16x32_bf16 v[56:59], v[144:147], v[236:239], v[56:59]
	v_mfma_f32_16x16x32_bf16 v[60:63], v[152:155], v[236:239], v[60:63]
	v_mfma_f32_16x16x32_bf16 v[0:3], v[148:151], v[188:191], v[0:3]
	v_mfma_f32_16x16x32_bf16 v[4:7], v[156:159], v[188:191], v[4:7]
	v_mfma_f32_16x16x32_bf16 v[8:11], v[148:151], v[224:227], v[8:11]
	v_mfma_f32_16x16x32_bf16 v[16:19], v[156:159], v[224:227], v[16:19]
	v_mfma_f32_16x16x32_bf16 v[32:35], v[148:151], v[232:235], v[32:35]
	v_mfma_f32_16x16x32_bf16 v[36:39], v[156:159], v[232:235], v[36:39]
	v_mfma_f32_16x16x32_bf16 v[56:59], v[148:151], v[240:243], v[56:59]
	v_mfma_f32_16x16x32_bf16 v[60:63], v[156:159], v[240:243], v[60:63]
	s_barrier
	s_add_i32 s65, s65, 2
	s_add_u32 s8, s8, 0x100
	s_addc_u32 s9, s9, 0
	s_add_u32 s46, s46, 0x100
	s_addc_u32 s47, s47, 0
	s_cmp_gt_u32 s65, 29
	s_cbranch_scc0 .LBB0_497
	s_setprio 0
	s_and_b64 vcc, exec, s[36:37]
	s_cbranch_vccz .LBB0_500
	s_barrier
